# dilated-group merge loop rewritten with 4 items in flight; indexer compaction fast path (no tie handling when all >= T are kept)
# speedup vs baseline: 1.4429x; 1.0069x over previous
; __device__ __forceinline__ unsigned pk2(float lo, float hi) { return f2bf(lo) | (f2bf(hi) << 16); }
; __device__ __forceinline__ void dilated_merge(const bf16_t* OG, const float* LSE, bf16_t* OA, int t, int hs, int lane) {
;     const float l0 = LSE[(size_t)t * 12 + hs], l1 = LSE[(size_t)t * 12 + 4 + hs], l2 = LSE[(size_t)t * 12 + 8 + hs];
;     const float mx = fmaxf(l0, fmaxf(l1, l2)); float w0 = __expf(l0 - mx), w1 = __expf(l1 - mx), w2 = __expf(l2 - mx);
;     const float inv = 1.f / (w0 + w1 + w2); w0 *= inv; w1 *= inv; w2 *= inv;
;     const size_t off = (size_t)t * 512 + hs * 128 + 2 * lane;
;     const unsigned v0 = *(const unsigned*)(OG + off), v1 = *(const unsigned*)(OG + (size_t)SEQ * 512 + off), v2 = *(const unsigned*)(OG + (size_t)2 * SEQ * 512 + off);
;     const float o0 = w0 * bf2f(v0 & 0xffffu) + w1 * bf2f(v1 & 0xffffu) + w2 * bf2f(v2 & 0xffffu);
;     const float o1 = w0 * __builtin_bit_cast(float, v0 & 0xffff0000u) + w1 * __builtin_bit_cast(float, v1 & 0xffff0000u) + w2 * __builtin_bit_cast(float, v2 & 0xffff0000u);
;     *(unsigned*)(OA + off) = pk2(o0, o1);
; }
; __global__ void __launch_bounds__(NTHREADS, 2) mega(Args a) {
;     ...
;                 for (int u = gw; u < SEQ * 4; u += NGW) dilated_merge(OG, LSE, OA, u >> 2, u & 3, lane);
.LBB0_128:
	s_mov_b32 s98, s8
	s_mov_b32 s101, 0
	s_ashr_i32 s0, s98, 2
	s_ashr_i32 s1, s0, 31
	s_mul_i32 s10, s0, 48
	s_mul_hi_i32 s9, s0, 48
	s_add_u32 s10, s4, s10
	s_addc_u32 s11, s5, s9
	global_load_dword v21, v161, s[10:11]
	global_load_dword v23, v161, s[10:11] offset:16
	global_load_dword v24, v161, s[10:11] offset:32
	s_lshl_b64 s[0:1], s[0:1], 10
	v_lshl_or_b32 v28, v0, 1, s0
	v_mov_b32_e32 v29, s1
	v_lshl_add_u64 v[30:31], s[30:31], 0, v[28:29]
	global_load_dword v34, v[30:31], off
	v_lshl_add_u64 v[30:31], s[16:17], 0, v[28:29]
	global_load_dword v35, v[30:31], off
	v_lshl_add_u64 v[30:31], s[22:23], 0, v[28:29]
	global_load_dword v36, v[30:31], off
	v_mov_b32_e32 v38, v28
	v_mov_b32_e32 v39, v29
	s_add_i32 s98, s98, s66
	s_add_i32 s101, s101, 1
	s_cmp_gt_i32 s98, 0xffff
	s_cbranch_scc1 .Lmg_ld_done
	s_ashr_i32 s0, s98, 2
	s_ashr_i32 s1, s0, 31
	s_mul_i32 s10, s0, 48
	s_mul_hi_i32 s9, s0, 48
	s_add_u32 s10, s4, s10
	s_addc_u32 s11, s5, s9
	global_load_dword v41, v161, s[10:11]
	global_load_dword v43, v161, s[10:11] offset:16
	global_load_dword v44, v161, s[10:11] offset:32
	s_lshl_b64 s[0:1], s[0:1], 10
	v_lshl_or_b32 v48, v0, 1, s0
	v_mov_b32_e32 v49, s1
	v_lshl_add_u64 v[50:51], s[30:31], 0, v[48:49]
	global_load_dword v54, v[50:51], off
	v_lshl_add_u64 v[50:51], s[16:17], 0, v[48:49]
	global_load_dword v55, v[50:51], off
	v_lshl_add_u64 v[50:51], s[22:23], 0, v[48:49]
	global_load_dword v56, v[50:51], off
	v_mov_b32_e32 v58, v48
	v_mov_b32_e32 v59, v49
	s_add_i32 s98, s98, s66
	s_add_i32 s101, s101, 1
	s_cmp_gt_i32 s98, 0xffff
	s_cbranch_scc1 .Lmg_ld_done
	s_ashr_i32 s0, s98, 2
	s_ashr_i32 s1, s0, 31
	s_mul_i32 s10, s0, 48
	s_mul_hi_i32 s9, s0, 48
	s_add_u32 s10, s4, s10
	s_addc_u32 s11, s5, s9
	global_load_dword v61, v161, s[10:11]
	global_load_dword v63, v161, s[10:11] offset:16
	global_load_dword v64, v161, s[10:11] offset:32
	s_lshl_b64 s[0:1], s[0:1], 10
	v_lshl_or_b32 v68, v0, 1, s0
	v_mov_b32_e32 v69, s1
	v_lshl_add_u64 v[70:71], s[30:31], 0, v[68:69]
	global_load_dword v74, v[70:71], off
	v_lshl_add_u64 v[70:71], s[16:17], 0, v[68:69]
	global_load_dword v75, v[70:71], off
	v_lshl_add_u64 v[70:71], s[22:23], 0, v[68:69]
	global_load_dword v76, v[70:71], off
	v_mov_b32_e32 v78, v68
	v_mov_b32_e32 v79, v69
	s_add_i32 s98, s98, s66
	s_add_i32 s101, s101, 1
	s_cmp_gt_i32 s98, 0xffff
	s_cbranch_scc1 .Lmg_ld_done
	s_ashr_i32 s0, s98, 2
	s_ashr_i32 s1, s0, 31
	s_mul_i32 s10, s0, 48
	s_mul_hi_i32 s9, s0, 48
	s_add_u32 s10, s4, s10
	s_addc_u32 s11, s5, s9
	global_load_dword v81, v161, s[10:11]
	global_load_dword v83, v161, s[10:11] offset:16
	global_load_dword v84, v161, s[10:11] offset:32
	s_lshl_b64 s[0:1], s[0:1], 10
	v_lshl_or_b32 v88, v0, 1, s0
	v_mov_b32_e32 v89, s1
	v_lshl_add_u64 v[90:91], s[30:31], 0, v[88:89]
	global_load_dword v94, v[90:91], off
	v_lshl_add_u64 v[90:91], s[16:17], 0, v[88:89]
	global_load_dword v95, v[90:91], off
	v_lshl_add_u64 v[90:91], s[22:23], 0, v[88:89]
	global_load_dword v96, v[90:91], off
	v_mov_b32_e32 v98, v88
	v_mov_b32_e32 v99, v89
	s_add_i32 s98, s98, s66
	s_add_i32 s101, s101, 1
.Lmg_ld_done:
	s_waitcnt vmcnt(0)
	v_max3_f32 v25, v21, v23, v24
	v_sub_f32_e32 v21, v21, v25
	v_mul_f32_e32 v21, 0x3fb8aa3b, v21
	v_exp_f32_e32 v22, v21
	v_sub_f32_e32 v21, v23, v25
	v_mul_f32_e32 v21, 0x3fb8aa3b, v21
	v_exp_f32_e32 v23, v21
	v_sub_f32_e32 v21, v24, v25
	v_mul_f32_e32 v21, 0x3fb8aa3b, v21
	v_exp_f32_e32 v21, v21
	v_add_f32_e32 v24, v22, v23
	v_add_f32_e32 v24, v21, v24
	v_div_scale_f32 v25, s[10:11], v24, v24, 1.0
	v_rcp_f32_e32 v26, v25
	s_nop 0
	v_fma_f32 v27, -v25, v26, 1.0
	v_fmac_f32_e32 v26, v27, v26
	v_div_scale_f32 v27, vcc, 1.0, v24, 1.0
	v_mul_f32_e32 v28, v27, v26
	v_fma_f32 v29, -v25, v28, v27
	v_fmac_f32_e32 v28, v29, v26
	v_fma_f32 v25, -v25, v28, v27
	v_div_fmas_f32 v25, v25, v26, v28
	s_nop 0
	v_div_fixup_f32 v24, v25, v24, 1.0
	v_mul_f32_e32 v26, v21, v24
	v_mov_b32_e32 v21, v34
	v_mov_b32_e32 v27, v35
	v_mov_b32_e32 v25, v36
	v_lshlrev_b32_e32 v32, 16, v21
	v_and_b32_e32 v33, 0xffff0000, v27
	v_lshlrev_b32_e32 v30, 16, v25
	v_and_b32_e32 v31, 0xffff0000, v25
	v_pk_mul_f32 v[22:23], v[22:23], v[24:25] op_sel_hi:[1,0]
	v_and_b32_e32 v24, 0xffff0000, v21
	v_lshlrev_b32_e32 v25, 16, v27
	v_pk_mul_f32 v[24:25], v[22:23], v[24:25]
	s_nop 0
	v_pk_fma_f32 v[22:23], v[22:23], v[32:33], v[24:25] op_sel:[0,0,1] op_sel_hi:[1,1,0]
	s_nop 0
	v_pk_fma_f32 v[22:23], v[26:27], v[30:31], v[22:23] op_sel_hi:[0,1,1]
	v_and_b32_sdwa v24, v22, v207 dst_sel:DWORD dst_unused:UNUSED_PAD src0_sel:WORD_1 src1_sel:DWORD
	v_and_b32_sdwa v21, v23, v207 dst_sel:DWORD dst_unused:UNUSED_PAD src0_sel:WORD_1 src1_sel:DWORD
	v_add3_u32 v22, v22, v24, s33
	v_add3_u32 v21, v23, v21, s33
	v_lshrrev_b32_e32 v22, 16, v22
	v_and_or_b32 v21, v21, s67, v22
	v_lshl_add_u64 v[22:23], s[62:63], 0, v[38:39]
	global_store_dword v[22:23], v21, off
	s_cmp_lt_u32 s101, 2
	s_cbranch_scc1 .Lmg_cp_done
; __device__ __forceinline__ unsigned pk2(float lo, float hi) { return f2bf(lo) | (f2bf(hi) << 16); }
; __device__ __forceinline__ void dilated_merge(const bf16_t* OG, const float* LSE, bf16_t* OA, int t, int hs, int lane) {
;     const float l0 = LSE[(size_t)t * 12 + hs], l1 = LSE[(size_t)t * 12 + 4 + hs], l2 = LSE[(size_t)t * 12 + 8 + hs];
;     const float mx = fmaxf(l0, fmaxf(l1, l2)); float w0 = __expf(l0 - mx), w1 = __expf(l1 - mx), w2 = __expf(l2 - mx);
;     const float inv = 1.f / (w0 + w1 + w2); w0 *= inv; w1 *= inv; w2 *= inv;
;     const size_t off = (size_t)t * 512 + hs * 128 + 2 * lane;
;     const unsigned v0 = *(const unsigned*)(OG + off), v1 = *(const unsigned*)(OG + (size_t)SEQ * 512 + off), v2 = *(const unsigned*)(OG + (size_t)2 * SEQ * 512 + off);
;     const float o0 = w0 * bf2f(v0 & 0xffffu) + w1 * bf2f(v1 & 0xffffu) + w2 * bf2f(v2 & 0xffffu);
;     const float o1 = w0 * __builtin_bit_cast(float, v0 & 0xffff0000u) + w1 * __builtin_bit_cast(float, v1 & 0xffff0000u) + w2 * __builtin_bit_cast(float, v2 & 0xffff0000u);
;     *(unsigned*)(OA + off) = pk2(o0, o1);
; }
; __global__ void __launch_bounds__(NTHREADS, 2) mega(Args a) {
;     ...
;                 for (int u = gw; u < SEQ * 4; u += NGW) dilated_merge(OG, LSE, OA, u >> 2, u & 3, lane);
	v_max3_f32 v45, v41, v43, v44
	v_sub_f32_e32 v41, v41, v45
	v_mul_f32_e32 v41, 0x3fb8aa3b, v41
	v_exp_f32_e32 v42, v41
	v_sub_f32_e32 v41, v43, v45
	v_mul_f32_e32 v41, 0x3fb8aa3b, v41
	v_exp_f32_e32 v43, v41
	v_sub_f32_e32 v41, v44, v45
	v_mul_f32_e32 v41, 0x3fb8aa3b, v41
	v_exp_f32_e32 v41, v41
	v_add_f32_e32 v44, v42, v43
	v_add_f32_e32 v44, v41, v44
	v_div_scale_f32 v45, s[10:11], v44, v44, 1.0
	v_rcp_f32_e32 v46, v45
	s_nop 0
	v_fma_f32 v47, -v45, v46, 1.0
	v_fmac_f32_e32 v46, v47, v46
	v_div_scale_f32 v47, vcc, 1.0, v44, 1.0
	v_mul_f32_e32 v48, v47, v46
	v_fma_f32 v49, -v45, v48, v47
	v_fmac_f32_e32 v48, v49, v46
	v_fma_f32 v45, -v45, v48, v47
	v_div_fmas_f32 v45, v45, v46, v48
	s_nop 0
	v_div_fixup_f32 v44, v45, v44, 1.0
	v_mul_f32_e32 v46, v41, v44
	v_mov_b32_e32 v41, v54
	v_mov_b32_e32 v47, v55
	v_mov_b32_e32 v45, v56
	v_lshlrev_b32_e32 v52, 16, v41
	v_and_b32_e32 v53, 0xffff0000, v47
	v_lshlrev_b32_e32 v50, 16, v45
	v_and_b32_e32 v51, 0xffff0000, v45
	v_pk_mul_f32 v[42:43], v[42:43], v[44:45] op_sel_hi:[1,0]
	v_and_b32_e32 v44, 0xffff0000, v41
	v_lshlrev_b32_e32 v45, 16, v47
	v_pk_mul_f32 v[44:45], v[42:43], v[44:45]
	s_nop 0
	v_pk_fma_f32 v[42:43], v[42:43], v[52:53], v[44:45] op_sel:[0,0,1] op_sel_hi:[1,1,0]
	s_nop 0
	v_pk_fma_f32 v[42:43], v[46:47], v[50:51], v[42:43] op_sel_hi:[0,1,1]
	v_and_b32_sdwa v44, v42, v207 dst_sel:DWORD dst_unused:UNUSED_PAD src0_sel:WORD_1 src1_sel:DWORD
	v_and_b32_sdwa v41, v43, v207 dst_sel:DWORD dst_unused:UNUSED_PAD src0_sel:WORD_1 src1_sel:DWORD
	v_add3_u32 v42, v42, v44, s33
	v_add3_u32 v41, v43, v41, s33
	v_lshrrev_b32_e32 v42, 16, v42
	v_and_or_b32 v41, v41, s67, v42
	v_lshl_add_u64 v[42:43], s[62:63], 0, v[58:59]
	global_store_dword v[42:43], v41, off
	s_cmp_lt_u32 s101, 3
	s_cbranch_scc1 .Lmg_cp_done
	v_max3_f32 v65, v61, v63, v64
	v_sub_f32_e32 v61, v61, v65
	v_mul_f32_e32 v61, 0x3fb8aa3b, v61
	v_exp_f32_e32 v62, v61
	v_sub_f32_e32 v61, v63, v65
	v_mul_f32_e32 v61, 0x3fb8aa3b, v61
	v_exp_f32_e32 v63, v61
	v_sub_f32_e32 v61, v64, v65
	v_mul_f32_e32 v61, 0x3fb8aa3b, v61
	v_exp_f32_e32 v61, v61
	v_add_f32_e32 v64, v62, v63
	v_add_f32_e32 v64, v61, v64
	v_div_scale_f32 v65, s[10:11], v64, v64, 1.0
	v_rcp_f32_e32 v66, v65
	s_nop 0
	v_fma_f32 v67, -v65, v66, 1.0
	v_fmac_f32_e32 v66, v67, v66
	v_div_scale_f32 v67, vcc, 1.0, v64, 1.0
	v_mul_f32_e32 v68, v67, v66
	v_fma_f32 v69, -v65, v68, v67
	v_fmac_f32_e32 v68, v69, v66
	v_fma_f32 v65, -v65, v68, v67
	v_div_fmas_f32 v65, v65, v66, v68
	s_nop 0
	v_div_fixup_f32 v64, v65, v64, 1.0
	v_mul_f32_e32 v66, v61, v64
	v_mov_b32_e32 v61, v74
	v_mov_b32_e32 v67, v75
	v_mov_b32_e32 v65, v76
	v_lshlrev_b32_e32 v72, 16, v61
	v_and_b32_e32 v73, 0xffff0000, v67
	v_lshlrev_b32_e32 v70, 16, v65
	v_and_b32_e32 v71, 0xffff0000, v65
	v_pk_mul_f32 v[62:63], v[62:63], v[64:65] op_sel_hi:[1,0]
	v_and_b32_e32 v64, 0xffff0000, v61
	v_lshlrev_b32_e32 v65, 16, v67
	v_pk_mul_f32 v[64:65], v[62:63], v[64:65]
	s_nop 0
	v_pk_fma_f32 v[62:63], v[62:63], v[72:73], v[64:65] op_sel:[0,0,1] op_sel_hi:[1,1,0]
	s_nop 0
	v_pk_fma_f32 v[62:63], v[66:67], v[70:71], v[62:63] op_sel_hi:[0,1,1]
	v_and_b32_sdwa v64, v62, v207 dst_sel:DWORD dst_unused:UNUSED_PAD src0_sel:WORD_1 src1_sel:DWORD
	v_and_b32_sdwa v61, v63, v207 dst_sel:DWORD dst_unused:UNUSED_PAD src0_sel:WORD_1 src1_sel:DWORD
	v_add3_u32 v62, v62, v64, s33
	v_add3_u32 v61, v63, v61, s33
	v_lshrrev_b32_e32 v62, 16, v62
	v_and_or_b32 v61, v61, s67, v62
	v_lshl_add_u64 v[62:63], s[62:63], 0, v[78:79]
	global_store_dword v[62:63], v61, off
	s_cmp_lt_u32 s101, 4
	s_cbranch_scc1 .Lmg_cp_done
	v_max3_f32 v85, v81, v83, v84
	v_sub_f32_e32 v81, v81, v85
	v_mul_f32_e32 v81, 0x3fb8aa3b, v81
	v_exp_f32_e32 v82, v81
	v_sub_f32_e32 v81, v83, v85
	v_mul_f32_e32 v81, 0x3fb8aa3b, v81
	v_exp_f32_e32 v83, v81
	v_sub_f32_e32 v81, v84, v85
	v_mul_f32_e32 v81, 0x3fb8aa3b, v81
	v_exp_f32_e32 v81, v81
	v_add_f32_e32 v84, v82, v83
	v_add_f32_e32 v84, v81, v84
	v_div_scale_f32 v85, s[10:11], v84, v84, 1.0
	v_rcp_f32_e32 v86, v85
	s_nop 0
	v_fma_f32 v87, -v85, v86, 1.0
	v_fmac_f32_e32 v86, v87, v86
	v_div_scale_f32 v87, vcc, 1.0, v84, 1.0
	v_mul_f32_e32 v88, v87, v86
	v_fma_f32 v89, -v85, v88, v87
	v_fmac_f32_e32 v88, v89, v86
	v_fma_f32 v85, -v85, v88, v87
	v_div_fmas_f32 v85, v85, v86, v88
	s_nop 0
	v_div_fixup_f32 v84, v85, v84, 1.0
	v_mul_f32_e32 v86, v81, v84
	v_mov_b32_e32 v81, v94
	v_mov_b32_e32 v87, v95
	v_mov_b32_e32 v85, v96
	v_lshlrev_b32_e32 v92, 16, v81
	v_and_b32_e32 v93, 0xffff0000, v87
	v_lshlrev_b32_e32 v90, 16, v85
	v_and_b32_e32 v91, 0xffff0000, v85
	v_pk_mul_f32 v[82:83], v[82:83], v[84:85] op_sel_hi:[1,0]
	v_and_b32_e32 v84, 0xffff0000, v81
	v_lshlrev_b32_e32 v85, 16, v87
	v_pk_mul_f32 v[84:85], v[82:83], v[84:85]
	s_nop 0
	v_pk_fma_f32 v[82:83], v[82:83], v[92:93], v[84:85] op_sel:[0,0,1] op_sel_hi:[1,1,0]
	s_nop 0
	v_pk_fma_f32 v[82:83], v[86:87], v[90:91], v[82:83] op_sel_hi:[0,1,1]
	v_and_b32_sdwa v84, v82, v207 dst_sel:DWORD dst_unused:UNUSED_PAD src0_sel:WORD_1 src1_sel:DWORD
	v_and_b32_sdwa v81, v83, v207 dst_sel:DWORD dst_unused:UNUSED_PAD src0_sel:WORD_1 src1_sel:DWORD
	v_add3_u32 v82, v82, v84, s33
	v_add3_u32 v81, v83, v81, s33
	v_lshrrev_b32_e32 v82, 16, v82
	v_and_or_b32 v81, v81, s67, v82
	v_lshl_add_u64 v[82:83], s[62:63], 0, v[98:99]
	global_store_dword v[82:83], v81, off
.Lmg_cp_done:
	s_mov_b32 s8, s98
	s_cmp_gt_i32 s8, 0xffff
	s_cbranch_scc0 .LBB0_128

; #define LAS __attribute__((address_space(3)))
; __device__ __forceinline__ void idx_compact(LAS float* bs, LAS unsigned* bi, int& cnt, float& tau, int lane) {
;     unsigned u[ICAP / 64], id[ICAP / 64];
; #pragma unroll
;     for (int i = 0; i < ICAP / 64; ++i) { const int e = i * 64 + lane; const bool in = e < cnt; u[i] = in ? f2sort(bs[e]) : 0u; id[i] = in ? bi[e] : 0u; }
;     unsigned T = 0u;
; #pragma unroll 1
;     ...
; #pragma unroll
;         for (int i = 0; i < ICAP / 64; ++i) c += __popcll(__ballot(u[i] >= cand));
;         if (c >= 256) T = cand; if (c == 256) break; }
.Lix_compact:
	v_add_u32_e32 v193, s79, v187
	v_subrev_u32_e32 v193, s82, v193
	ds_read2st64_b32 v[240:241], v193 offset0:0 offset1:1
	ds_read2st64_b32 v[242:243], v193 offset0:2 offset1:3
	ds_read2st64_b32 v[244:245], v193 offset0:4 offset1:5
	ds_read2st64_b32 v[246:247], v193 offset0:6 offset1:7
	ds_read2st64_b32 v[214:215], v193 offset0:8 offset1:9
	ds_read2st64_b32 v[216:217], v193 offset0:10 offset1:11
	ds_read2st64_b32 v[218:219], v193 offset0:12 offset1:13
	ds_read2st64_b32 v[220:221], v193 offset0:14 offset1:15
	s_waitcnt lgkmcnt(0)
	v_ashrrev_i32_e32 v190, 31, v240
	v_or_b32_e32 v190, 0x80000000, v190
	v_xor_b32_e32 v194, v240, v190
	v_ashrrev_i32_e32 v190, 31, v241
	v_or_b32_e32 v190, 0x80000000, v190
	v_xor_b32_e32 v195, v241, v190
	v_ashrrev_i32_e32 v190, 31, v242
	v_or_b32_e32 v190, 0x80000000, v190
	v_xor_b32_e32 v196, v242, v190
	v_ashrrev_i32_e32 v190, 31, v243
	v_or_b32_e32 v190, 0x80000000, v190
	v_xor_b32_e32 v197, v243, v190
	v_ashrrev_i32_e32 v190, 31, v244
	s_sub_i32 s0, s80, 256
	v_or_b32_e32 v190, 0x80000000, v190
	v_cmp_gt_i32_e32 vcc, s0, v182
	v_xor_b32_e32 v198, v244, v190
	s_nop 0
	v_cndmask_b32_e32 v198, 0, v198, vcc
	v_ashrrev_i32_e32 v190, 31, v245
	s_sub_i32 s0, s80, 320
	v_or_b32_e32 v190, 0x80000000, v190
	v_cmp_gt_i32_e32 vcc, s0, v182
	v_xor_b32_e32 v199, v245, v190
	s_nop 0
	v_cndmask_b32_e32 v199, 0, v199, vcc
	v_ashrrev_i32_e32 v190, 31, v246
	s_sub_i32 s0, s80, 384
	v_or_b32_e32 v190, 0x80000000, v190
	v_cmp_gt_i32_e32 vcc, s0, v182
	v_xor_b32_e32 v200, v246, v190
	s_nop 0
	v_cndmask_b32_e32 v200, 0, v200, vcc
	v_ashrrev_i32_e32 v190, 31, v247
	s_sub_i32 s0, s80, 448
	v_or_b32_e32 v190, 0x80000000, v190
	v_cmp_gt_i32_e32 vcc, s0, v182
	v_xor_b32_e32 v201, v247, v190
	s_nop 0
	v_cndmask_b32_e32 v201, 0, v201, vcc
	v_max_u32_e32 v190, v194, v195
	v_max3_u32 v190, v190, v196, v197
	v_max3_u32 v190, v190, v198, v199
	v_max3_u32 v190, v190, v200, v201
	s_nop 1
	v_max_u32_dpp v190, v190, v190 row_ror:8 row_mask:0xf bank_mask:0xf bound_ctrl:1
	s_nop 1
	v_max_u32_dpp v190, v190, v190 row_ror:4 row_mask:0xf bank_mask:0xf bound_ctrl:1
	s_nop 1
	v_max_u32_dpp v190, v190, v190 quad_perm:[2,3,0,1] row_mask:0xf bank_mask:0xf bound_ctrl:1
	s_nop 1
	v_max_u32_dpp v190, v190, v190 quad_perm:[1,0,3,2] row_mask:0xf bank_mask:0xf bound_ctrl:1
	v_mov_b32_e32 v191, v190
	s_nop 1
	v_permlane16_swap_b32_e32 v190, v191
	s_nop 1
	v_max_u32_e32 v190, v190, v191
	v_mov_b32_e32 v191, v190
	s_nop 1
	v_permlane32_swap_b32_e32 v190, v191
	s_nop 1
	v_max_u32_e32 v190, v190, v191
	s_nop 1
	v_readfirstlane_b32 s0, v190
	s_mov_b32 s100, s80
	s_nop 2
	s_xor_b32 s1, s0, s56
	s_cmp_eq_u32 s1, 0
	s_cbranch_scc1 .Lix_cs_done
	s_flbit_i32_b32 s1, s1
	s_lshr_b32 s0, -1, s1
	s_andn2_b32 s56, s56, s0
	s_sub_i32 s83, 31, s1

; __device__ __forceinline__ int lane_prefix(unsigned long long mask) { return __builtin_amdgcn_mbcnt_hi((unsigned)(mask >> 32), __builtin_amdgcn_mbcnt_lo((unsigned)mask, 0)); }
; __device__ __forceinline__ void idx_compact(LAS float* bs, LAS unsigned* bi, int& cnt, float& tau, int lane) {
;     ...
;     int ngt = 0;
; #pragma unroll
;     for (int i = 0; i < ICAP / 64; ++i) ngt += __popcll(__ballot(u[i] > T));
;     const int need_eq = 256 - ngt;
;     int base = 0, eqbase = 0;
;     __builtin_amdgcn_wave_barrier();
; #pragma unroll
;     for (int i = 0; i < ICAP / 64; ++i) {
;         const bool gt = u[i] > T, eq = u[i] == T;
;         const unsigned long long em = __ballot(eq); const int eqpos = eqbase + lane_prefix(em); eqbase += __popcll(em);
;         const bool keep = gt || (eq && eqpos < need_eq);
;         const unsigned long long km = __ballot(keep); const int pos = base + lane_prefix(km); base += __popcll(km);
;         if (keep) { bs[pos] = sort2f(u[i]); bi[pos] = id[i]; }
;     }
.Lix_cs_done:
	v_cmp_lt_u32_e64 s[64:65], s56, v194
	v_cmp_lt_u32_e64 s[30:31], s56, v195
	v_cmp_lt_u32_e64 s[36:37], s56, v196
	v_cmp_lt_u32_e64 s[62:63], s56, v197
	v_cmp_lt_u32_e64 s[68:69], s56, v198
	v_cmp_lt_u32_e64 s[70:71], s56, v199
	v_cmp_lt_u32_e64 s[72:73], s56, v200
	v_cmp_lt_u32_e64 s[74:75], s56, v201
	s_bcnt1_i32_b64 s0, s[64:65]
	s_bcnt1_i32_b64 s1, s[30:31]
	s_add_i32 s0, s0, s1
	s_bcnt1_i32_b64 s1, s[36:37]
	s_add_i32 s0, s0, s1
	s_bcnt1_i32_b64 s1, s[62:63]
	s_add_i32 s0, s0, s1
	s_bcnt1_i32_b64 s1, s[68:69]
	s_add_i32 s0, s0, s1
	s_bcnt1_i32_b64 s1, s[70:71]
	s_add_i32 s0, s0, s1
	s_bcnt1_i32_b64 s1, s[72:73]
	s_add_i32 s0, s0, s1
	s_bcnt1_i32_b64 s1, s[74:75]
	s_add_i32 s0, s0, s1
	s_cmp_le_u32 s100, s19
	s_cselect_b32 s80, s100, 0x100
	s_sub_i32 s19, s80, s0
	s_cmp_lg_u32 s80, s100
	s_cbranch_scc1 .Lix_part_slow
	v_cmp_le_u32_e64 s[64:65], s56, v194
	v_cmp_le_u32_e64 s[30:31], s56, v195
	v_cmp_le_u32_e64 s[36:37], s56, v196
	v_cmp_le_u32_e64 s[62:63], s56, v197
	v_cmp_le_u32_e64 s[68:69], s56, v198
	v_cmp_le_u32_e64 s[70:71], s56, v199
	v_cmp_le_u32_e64 s[72:73], s56, v200
	v_cmp_le_u32_e64 s[74:75], s56, v201
	s_mov_b64 s[4:5], exec
	s_mov_b32 s99, 0
	v_mbcnt_lo_u32_b32 v191, s64, 0
	v_mbcnt_hi_u32_b32 v191, s65, v191
	v_add_u32_e32 v191, s99, v191
	v_lshl_add_u32 v191, v191, 2, s79
	s_mov_b64 exec, s[64:65]
	ds_write2st64_b32 v191, v240, v214 offset1:8
	s_mov_b64 exec, s[4:5]
	s_bcnt1_i32_b64 s83, s[64:65]
	s_add_i32 s99, s99, s83
	v_mbcnt_lo_u32_b32 v191, s30, 0
	v_mbcnt_hi_u32_b32 v191, s31, v191
	v_add_u32_e32 v191, s99, v191
	v_lshl_add_u32 v191, v191, 2, s79
	s_mov_b64 exec, s[30:31]
	ds_write2st64_b32 v191, v241, v215 offset1:8
	s_mov_b64 exec, s[4:5]
	s_bcnt1_i32_b64 s83, s[30:31]
	s_add_i32 s99, s99, s83
	v_mbcnt_lo_u32_b32 v191, s36, 0
	v_mbcnt_hi_u32_b32 v191, s37, v191
	v_add_u32_e32 v191, s99, v191
	v_lshl_add_u32 v191, v191, 2, s79
	s_mov_b64 exec, s[36:37]
	ds_write2st64_b32 v191, v242, v216 offset1:8
	s_mov_b64 exec, s[4:5]
	s_bcnt1_i32_b64 s83, s[36:37]
	s_add_i32 s99, s99, s83
	v_mbcnt_lo_u32_b32 v191, s62, 0
	v_mbcnt_hi_u32_b32 v191, s63, v191
	v_add_u32_e32 v191, s99, v191
	v_lshl_add_u32 v191, v191, 2, s79
	s_mov_b64 exec, s[62:63]
	ds_write2st64_b32 v191, v243, v217 offset1:8
	s_mov_b64 exec, s[4:5]
	s_bcnt1_i32_b64 s83, s[62:63]
	s_add_i32 s99, s99, s83
	v_mbcnt_lo_u32_b32 v191, s68, 0
	v_mbcnt_hi_u32_b32 v191, s69, v191
	v_add_u32_e32 v191, s99, v191
	v_lshl_add_u32 v191, v191, 2, s79
	s_mov_b64 exec, s[68:69]
	ds_write2st64_b32 v191, v244, v218 offset1:8
	s_mov_b64 exec, s[4:5]
	s_bcnt1_i32_b64 s83, s[68:69]
	s_add_i32 s99, s99, s83
	v_mbcnt_lo_u32_b32 v191, s70, 0
	v_mbcnt_hi_u32_b32 v191, s71, v191
	v_add_u32_e32 v191, s99, v191
	v_lshl_add_u32 v191, v191, 2, s79
	s_mov_b64 exec, s[70:71]
	ds_write2st64_b32 v191, v245, v219 offset1:8
	s_mov_b64 exec, s[4:5]
	s_bcnt1_i32_b64 s83, s[70:71]
	s_add_i32 s99, s99, s83
	v_mbcnt_lo_u32_b32 v191, s72, 0
	v_mbcnt_hi_u32_b32 v191, s73, v191
	v_add_u32_e32 v191, s99, v191
	v_lshl_add_u32 v191, v191, 2, s79
	s_mov_b64 exec, s[72:73]
	ds_write2st64_b32 v191, v246, v220 offset1:8
	s_mov_b64 exec, s[4:5]
	s_bcnt1_i32_b64 s83, s[72:73]
	s_add_i32 s99, s99, s83
	v_mbcnt_lo_u32_b32 v191, s74, 0
	v_mbcnt_hi_u32_b32 v191, s75, v191
	v_add_u32_e32 v191, s99, v191
	v_lshl_add_u32 v191, v191, 2, s79
	s_mov_b64 exec, s[74:75]
	ds_write2st64_b32 v191, v247, v221 offset1:8
	s_mov_b64 exec, s[4:5]
	s_bcnt1_i32_b64 s83, s[74:75]
	s_add_i32 s99, s99, s83
	s_branch .Lix_part_done
; __device__ __forceinline__ int lane_prefix(unsigned long long mask) { return __builtin_amdgcn_mbcnt_hi((unsigned)(mask >> 32), __builtin_amdgcn_mbcnt_lo((unsigned)mask, 0)); }
; __device__ __forceinline__ void idx_compact(LAS float* bs, LAS unsigned* bi, int& cnt, float& tau, int lane) {
;     ...
;     int base = 0, eqbase = 0;
;     __builtin_amdgcn_wave_barrier();
; #pragma unroll
;     for (int i = 0; i < ICAP / 64; ++i) {
;         const bool gt = u[i] > T, eq = u[i] == T;
;         const unsigned long long em = __ballot(eq); const int eqpos = eqbase + lane_prefix(em); eqbase += __popcll(em);
;         const bool keep = gt || (eq && eqpos < need_eq);
;         const unsigned long long km = __ballot(keep); const int pos = base + lane_prefix(km); base += __popcll(km);
;         if (keep) { bs[pos] = sort2f(u[i]); bi[pos] = id[i]; }
;     }
;     __builtin_amdgcn_wave_barrier();
;     cnt = 256; tau = sort2f(T);
; }
.Lix_part_slow:
	s_mov_b32 s98, 0
	s_mov_b32 s99, 0
	s_mov_b64 s[4:5], exec
	v_cmp_eq_u32_e64 s[0:1], s56, v194
	s_nop 1
	v_mbcnt_lo_u32_b32 v190, s0, 0
	v_mbcnt_hi_u32_b32 v190, s1, v190
	v_add_u32_e32 v190, s98, v190
	v_cmp_gt_i32_e32 vcc, s19, v190
	s_bcnt1_i32_b64 s83, s[0:1]
	s_add_i32 s98, s98, s83
	s_and_b64 s[0:1], s[0:1], vcc
	s_or_b64 s[0:1], s[0:1], s[64:65]
	v_mbcnt_lo_u32_b32 v191, s0, 0
	v_mbcnt_hi_u32_b32 v191, s1, v191
	v_add_u32_e32 v191, s99, v191
	v_lshl_add_u32 v191, v191, 2, s79
	s_mov_b64 exec, s[0:1]
	ds_write2st64_b32 v191, v240, v214 offset1:8
	s_mov_b64 exec, s[4:5]
	s_bcnt1_i32_b64 s83, s[0:1]
	s_add_i32 s99, s99, s83
	v_cmp_eq_u32_e64 s[0:1], s56, v195
	s_nop 1
	v_mbcnt_lo_u32_b32 v190, s0, 0
	v_mbcnt_hi_u32_b32 v190, s1, v190
	v_add_u32_e32 v190, s98, v190
	v_cmp_gt_i32_e32 vcc, s19, v190
	s_bcnt1_i32_b64 s83, s[0:1]
	s_add_i32 s98, s98, s83
	s_and_b64 s[0:1], s[0:1], vcc
	s_or_b64 s[0:1], s[0:1], s[30:31]
	v_mbcnt_lo_u32_b32 v191, s0, 0
	v_mbcnt_hi_u32_b32 v191, s1, v191
	v_add_u32_e32 v191, s99, v191
	v_lshl_add_u32 v191, v191, 2, s79
	s_mov_b64 exec, s[0:1]
	ds_write2st64_b32 v191, v241, v215 offset1:8
	s_mov_b64 exec, s[4:5]
	s_bcnt1_i32_b64 s83, s[0:1]
	s_add_i32 s99, s99, s83
	v_cmp_eq_u32_e64 s[0:1], s56, v196
	s_nop 1
	v_mbcnt_lo_u32_b32 v190, s0, 0
	v_mbcnt_hi_u32_b32 v190, s1, v190
	v_add_u32_e32 v190, s98, v190
	v_cmp_gt_i32_e32 vcc, s19, v190
	s_bcnt1_i32_b64 s83, s[0:1]
	s_add_i32 s98, s98, s83
	s_and_b64 s[0:1], s[0:1], vcc
	s_or_b64 s[0:1], s[0:1], s[36:37]
	v_mbcnt_lo_u32_b32 v191, s0, 0
	v_mbcnt_hi_u32_b32 v191, s1, v191
	v_add_u32_e32 v191, s99, v191
	v_lshl_add_u32 v191, v191, 2, s79
	s_mov_b64 exec, s[0:1]
	ds_write2st64_b32 v191, v242, v216 offset1:8
	s_mov_b64 exec, s[4:5]
	s_bcnt1_i32_b64 s83, s[0:1]
	s_add_i32 s99, s99, s83
	v_cmp_eq_u32_e64 s[0:1], s56, v197
	s_nop 1
	v_mbcnt_lo_u32_b32 v190, s0, 0
	v_mbcnt_hi_u32_b32 v190, s1, v190
	v_add_u32_e32 v190, s98, v190
	v_cmp_gt_i32_e32 vcc, s19, v190
	s_bcnt1_i32_b64 s83, s[0:1]
	s_add_i32 s98, s98, s83
	s_and_b64 s[0:1], s[0:1], vcc
	s_or_b64 s[0:1], s[0:1], s[62:63]
	v_mbcnt_lo_u32_b32 v191, s0, 0
	v_mbcnt_hi_u32_b32 v191, s1, v191
	v_add_u32_e32 v191, s99, v191
	v_lshl_add_u32 v191, v191, 2, s79
	s_mov_b64 exec, s[0:1]
	ds_write2st64_b32 v191, v243, v217 offset1:8
	s_mov_b64 exec, s[4:5]
	s_bcnt1_i32_b64 s83, s[0:1]
	s_add_i32 s99, s99, s83
	v_cmp_eq_u32_e64 s[0:1], s56, v198
	s_nop 1
	v_mbcnt_lo_u32_b32 v190, s0, 0
	v_mbcnt_hi_u32_b32 v190, s1, v190
	v_add_u32_e32 v190, s98, v190
	v_cmp_gt_i32_e32 vcc, s19, v190
	s_bcnt1_i32_b64 s83, s[0:1]
	s_add_i32 s98, s98, s83
	s_and_b64 s[0:1], s[0:1], vcc
	s_or_b64 s[0:1], s[0:1], s[68:69]
	v_mbcnt_lo_u32_b32 v191, s0, 0
	v_mbcnt_hi_u32_b32 v191, s1, v191
	v_add_u32_e32 v191, s99, v191
	v_lshl_add_u32 v191, v191, 2, s79
	s_mov_b64 exec, s[0:1]
	ds_write2st64_b32 v191, v244, v218 offset1:8
	s_mov_b64 exec, s[4:5]
	s_bcnt1_i32_b64 s83, s[0:1]
	s_add_i32 s99, s99, s83
	v_cmp_eq_u32_e64 s[0:1], s56, v199
	s_nop 1
	v_mbcnt_lo_u32_b32 v190, s0, 0
	v_mbcnt_hi_u32_b32 v190, s1, v190
	v_add_u32_e32 v190, s98, v190
	v_cmp_gt_i32_e32 vcc, s19, v190
	s_bcnt1_i32_b64 s83, s[0:1]
	s_add_i32 s98, s98, s83
	s_and_b64 s[0:1], s[0:1], vcc
	s_or_b64 s[0:1], s[0:1], s[70:71]
	v_mbcnt_lo_u32_b32 v191, s0, 0
	v_mbcnt_hi_u32_b32 v191, s1, v191
	v_add_u32_e32 v191, s99, v191
	v_lshl_add_u32 v191, v191, 2, s79
	s_mov_b64 exec, s[0:1]
	ds_write2st64_b32 v191, v245, v219 offset1:8
	s_mov_b64 exec, s[4:5]
	s_bcnt1_i32_b64 s83, s[0:1]
	s_add_i32 s99, s99, s83
	v_cmp_eq_u32_e64 s[0:1], s56, v200
	s_nop 1
	v_mbcnt_lo_u32_b32 v190, s0, 0
	v_mbcnt_hi_u32_b32 v190, s1, v190
	v_add_u32_e32 v190, s98, v190
	v_cmp_gt_i32_e32 vcc, s19, v190
	s_bcnt1_i32_b64 s83, s[0:1]
	s_add_i32 s98, s98, s83
	s_and_b64 s[0:1], s[0:1], vcc
	s_or_b64 s[0:1], s[0:1], s[72:73]
	v_mbcnt_lo_u32_b32 v191, s0, 0
	v_mbcnt_hi_u32_b32 v191, s1, v191
	v_add_u32_e32 v191, s99, v191
	v_lshl_add_u32 v191, v191, 2, s79
	s_mov_b64 exec, s[0:1]
	ds_write2st64_b32 v191, v246, v220 offset1:8
	s_mov_b64 exec, s[4:5]
	s_bcnt1_i32_b64 s83, s[0:1]
	s_add_i32 s99, s99, s83
	v_cmp_eq_u32_e64 s[0:1], s56, v201
	s_nop 1
	v_mbcnt_lo_u32_b32 v190, s0, 0
	v_mbcnt_hi_u32_b32 v190, s1, v190
	v_add_u32_e32 v190, s98, v190
	v_cmp_gt_i32_e32 vcc, s19, v190
	s_bcnt1_i32_b64 s83, s[0:1]
	s_add_i32 s98, s98, s83
	s_and_b64 s[0:1], s[0:1], vcc
	s_or_b64 s[0:1], s[0:1], s[74:75]
	v_mbcnt_lo_u32_b32 v191, s0, 0
	v_mbcnt_hi_u32_b32 v191, s1, v191
	v_add_u32_e32 v191, s99, v191
	v_lshl_add_u32 v191, v191, 2, s79
	s_mov_b64 exec, s[0:1]
	ds_write2st64_b32 v191, v247, v221 offset1:8
	s_mov_b64 exec, s[4:5]
	s_bcnt1_i32_b64 s83, s[0:1]
	s_add_i32 s99, s99, s83
.Lix_part_done:
	s_ashr_i32 s0, s56, 31
	s_not_b32 s0, s0
	s_or_b32 s0, s0, 0x80000000
	s_xor_b32 s81, s56, s0
	s_cmp_eq_u32 s78, 0
	s_cbranch_scc1 .Lix_ret0
	s_cmp_eq_u32 s78, 1
	s_cbranch_scc1 .Lix_ret1
	s_cmp_eq_u32 s78, 2
	s_cbranch_scc1 .Lix_ret2
	s_cmp_eq_u32 s78, 3
	s_cbranch_scc1 .Lix_ret3
	s_cmp_eq_u32 s78, 4
	s_cbranch_scc1 .Lix_ret4
	s_cmp_eq_u32 s78, 5
	s_cbranch_scc1 .Lix_ret5
	s_cmp_eq_u32 s78, 6
	s_cbranch_scc1 .Lix_ret6
	s_cmp_eq_u32 s78, 7
	s_cbranch_scc1 .Lix_ret7
	s_cmp_eq_u32 s78, 8
	s_cbranch_scc1 .Lix_ret8
	s_cmp_eq_u32 s78, 9
	s_cbranch_scc1 .Lix_ret9
	s_cmp_eq_u32 s78, 10
	s_cbranch_scc1 .Lix_ret10
	s_cmp_eq_u32 s78, 11
	s_cbranch_scc1 .Lix_ret11
	s_cmp_eq_u32 s78, 12
	s_cbranch_scc1 .Lix_ret12
	s_cmp_eq_u32 s78, 13
	s_cbranch_scc1 .Lix_ret13
	s_cmp_eq_u32 s78, 14
	s_cbranch_scc1 .Lix_ret14
	s_cmp_eq_u32 s78, 15
	s_cbranch_scc1 .Lix_ret15
	s_cmp_eq_u32 s78, 16
	s_cbranch_scc1 .Lix_ret16
	s_cmp_eq_u32 s78, 17
	s_cbranch_scc1 .Lix_ret17
	s_cmp_eq_u32 s78, 18
	s_cbranch_scc1 .Lix_ret18
	s_cmp_eq_u32 s78, 19
	s_cbranch_scc1 .Lix_ret19
	s_endpgm
